# P12 fused epilogue first half: row-sum atomics of groups 0..6 issued behind the next group's residual loads (no load waits behind an atomic round trip); on top of the adjacent conv-unit pairing
# speedup vs baseline: 1.0052x; 1.0014x over previous
;     __device__ __forceinline__ void fused(f32x4 (&acc)[2][2][4][2], const Unit& u, int wr, int wc, int fr, int fq, PG8_LAS unsigned char* lds, int wid, int lane) const {
;     ...
;             for (int m = 0; m < 4; ++m) { const int row = u.pm * BM + ai * HALF + wr * 64 + m * 16 + fr; const size_t off = (size_t)row * ldc + col0; float ss = 0.f;
; #pragma unroll
;                 for (int bj = 0; bj < 2; ++bj)
; #pragma unroll
;                     for (int n = 0; n < 2; ++n) { const u32x2 w = *(const u32x2*)(xb + off + bj * HALF + n * 16);
;                         const f32x4 bs = (f32x4){__uint_as_float(w.x << 16), __uint_as_float(w.x & 0xffff0000u), __uint_as_float(w.y << 16), __uint_as_float(w.y & 0xffff0000u)};
;                         const f32x4 v = bs + acc[ai][bj][m][n]; acc[ai][bj][m][n] = v; ss += (v[0] * v[0] + v[1] * v[1]) + (v[2] * v[2] + v[3] * v[3]); }
;                 ss += __shfl_xor(ss, 16); ss += __shfl_xor(ss, 32); if (fq == 0) atomicAdd(rowsq + row, ss); }
.LBB0_1032:
	s_add_u32 s0, s84, 0x30000
	s_addc_u32 s1, s85, 0
	s_lshl_b32 s2, s10, 8
	s_add_i32 s2, s2, s39
	v_lshlrev_b32_e32 v128, 2, v144
	v_or_b32_e32 v130, s2, v145
	v_lshl_or_b32 v128, s44, 8, v128
	v_ashrrev_i32_e32 v131, 31, v130
	v_or_b32_e32 v128, s41, v128
	v_lshlrev_b64 v[132:133], 11, v[130:131]
	v_ashrrev_i32_e32 v129, 31, v128
	v_lshl_add_u64 v[132:133], s[96:97], 0, v[132:133]
	v_lshl_add_u64 v[132:133], v[128:129], 1, v[132:133]
	s_barrier
	global_load_dwordx2 v[134:135], v[132:133], off
	global_load_dwordx2 v[136:137], v[132:133], off offset:32
	global_load_dwordx2 v[138:139], v[132:133], off offset:256
	s_nop 0
	global_load_dwordx2 v[132:133], v[132:133], off offset:288
	v_mbcnt_lo_u32_b32 v140, -1, 0
	v_mbcnt_hi_u32_b32 v145, -1, v140
	v_and_b32_e32 v141, 64, v145
	v_xor_b32_e32 v140, 16, v145
	v_add_u32_e32 v152, 64, v141
	v_cmp_lt_i32_e32 vcc, v140, v152
	s_waitcnt vmcnt(0)
	v_and_b32_e32 v141, 0xffff0000, v134
	v_cndmask_b32_e32 v140, v145, v140, vcc
	v_lshlrev_b32_e32 v176, 2, v140
	v_lshlrev_b32_e32 v140, 16, v134
	v_lshlrev_b32_e32 v134, 16, v135
	v_and_b32_e32 v135, 0xffff0000, v135
	v_lshlrev_b32_e32 v142, 16, v136
	v_and_b32_e32 v143, 0xffff0000, v136
	v_lshlrev_b32_e32 v136, 16, v137
	v_and_b32_e32 v137, 0xffff0000, v137
	v_lshlrev_b32_e32 v146, 16, v138
	v_and_b32_e32 v147, 0xffff0000, v138
	v_lshlrev_b32_e32 v138, 16, v139
	v_and_b32_e32 v139, 0xffff0000, v139
	v_lshlrev_b32_e32 v148, 16, v132
	v_and_b32_e32 v149, 0xffff0000, v132
	v_lshlrev_b32_e32 v150, 16, v133
	v_and_b32_e32 v151, 0xffff0000, v133
	v_pk_add_f32 v[126:127], v[126:127], v[134:135]
	v_pk_add_f32 v[132:133], v[124:125], v[140:141]
	v_pk_add_f32 v[122:123], v[122:123], v[136:137]
	v_pk_add_f32 v[124:125], v[120:121], v[142:143]
	v_pk_add_f32 v[118:119], v[118:119], v[138:139]
	v_pk_add_f32 v[116:117], v[116:117], v[146:147]
	v_mul_f32_e32 v120, v133, v133
	v_mul_f32_e32 v121, v127, v127
	v_mul_f32_e32 v134, v125, v125
	v_mul_f32_e32 v135, v123, v123
	v_pk_add_f32 v[114:115], v[114:115], v[150:151]
	v_pk_add_f32 v[112:113], v[112:113], v[148:149]
	v_mul_f32_e32 v136, v117, v117
	v_mul_f32_e32 v137, v119, v119
	v_fmac_f32_e32 v120, v132, v132
	v_fmac_f32_e32 v121, v126, v126
	v_fmac_f32_e32 v134, v124, v124
	v_fmac_f32_e32 v135, v122, v122
	v_mul_f32_e32 v138, v113, v113
	v_mul_f32_e32 v139, v115, v115
	v_fmac_f32_e32 v136, v116, v116
	v_fmac_f32_e32 v137, v118, v118
	v_add_f32_e32 v120, v120, v121
	v_add_f32_e32 v121, v134, v135
	v_fmac_f32_e32 v138, v112, v112
	v_fmac_f32_e32 v139, v114, v114
	v_add_f32_e32 v134, v136, v137
	v_add_f32_e32 v120, v120, v121
	v_add_f32_e32 v120, v120, v134
	v_add_f32_e32 v121, v138, v139
	v_add_f32_e32 v120, v120, v121
	ds_bpermute_b32 v121, v176, v120
	v_xor_b32_e32 v134, 32, v145
	v_cmp_lt_i32_e32 vcc, v134, v152
	s_waitcnt lgkmcnt(0)
	v_add_f32_e32 v120, v120, v121
	v_cndmask_b32_e32 v134, v145, v134, vcc
	v_lshlrev_b32_e32 v177, 2, v134
	ds_bpermute_b32 v121, v177, v120
	v_cmp_eq_u32_e32 vcc, 0, v144
	v_lshl_add_u64 v[134:135], v[130:131], 2, s[0:1]
	s_mov_b64 s[98:99], vcc
	s_and_saveexec_b64 s[2:3], vcc
	s_cbranch_execz .LBB0_1034
	s_waitcnt lgkmcnt(0)
	v_add_f32_e32 v120, v120, v121
	v_mov_b32_e32 v218, v120
	v_mov_b32_e32 v216, v134
	v_mov_b32_e32 v217, v135
.LBB0_1034:
	s_or_b64 exec, exec, s[2:3]
	v_or_b32_e32 v120, 16, v130
	s_waitcnt lgkmcnt(0)
	v_ashrrev_i32_e32 v121, 31, v120
	v_lshlrev_b64 v[136:137], 11, v[120:121]
	v_lshl_add_u64 v[136:137], s[96:97], 0, v[136:137]
	v_lshl_add_u64 v[136:137], v[128:129], 1, v[136:137]
	global_load_dwordx2 v[138:139], v[136:137], off
	global_load_dwordx2 v[140:141], v[136:137], off offset:32
	global_load_dwordx2 v[142:143], v[136:137], off offset:256
	s_nop 0
	global_load_dwordx2 v[136:137], v[136:137], off offset:288
	s_and_saveexec_b64 s[2:3], s[98:99]
	global_atomic_add_f32 v[216:217], v218, off
	s_or_b64 exec, exec, s[2:3]
	s_waitcnt vmcnt(4)
	v_lshlrev_b32_e32 v144, 16, v138
	v_and_b32_e32 v145, 0xffff0000, v138
	v_lshlrev_b32_e32 v138, 16, v139
	v_and_b32_e32 v139, 0xffff0000, v139
	s_waitcnt vmcnt(3)
	v_lshlrev_b32_e32 v146, 16, v140
	v_and_b32_e32 v147, 0xffff0000, v140
	v_lshlrev_b32_e32 v140, 16, v141
	v_and_b32_e32 v141, 0xffff0000, v141
	s_waitcnt vmcnt(2)
	v_lshlrev_b32_e32 v148, 16, v142
	v_and_b32_e32 v149, 0xffff0000, v142
	v_lshlrev_b32_e32 v142, 16, v143
	v_and_b32_e32 v143, 0xffff0000, v143
	s_waitcnt vmcnt(1)
	v_lshlrev_b32_e32 v150, 16, v136
	v_and_b32_e32 v151, 0xffff0000, v136
	v_lshlrev_b32_e32 v152, 16, v137
	v_and_b32_e32 v153, 0xffff0000, v137
	v_pk_add_f32 v[110:111], v[110:111], v[138:139]
	v_pk_add_f32 v[136:137], v[108:109], v[144:145]
	v_pk_add_f32 v[106:107], v[106:107], v[140:141]
	v_pk_add_f32 v[108:109], v[104:105], v[146:147]
	v_pk_add_f32 v[102:103], v[102:103], v[142:143]
	v_pk_add_f32 v[100:101], v[100:101], v[148:149]
	v_mul_f32_e32 v104, v137, v137
	v_mul_f32_e32 v105, v111, v111
	v_mul_f32_e32 v131, v109, v109
	v_mul_f32_e32 v138, v107, v107
	v_pk_add_f32 v[98:99], v[98:99], v[152:153]
	v_pk_add_f32 v[96:97], v[96:97], v[150:151]
	v_mul_f32_e32 v139, v101, v101
	v_mul_f32_e32 v140, v103, v103
	v_fmac_f32_e32 v104, v136, v136
	v_fmac_f32_e32 v105, v110, v110
	v_fmac_f32_e32 v131, v108, v108
	v_fmac_f32_e32 v138, v106, v106
	v_mul_f32_e32 v141, v97, v97
	v_mul_f32_e32 v142, v99, v99
	v_fmac_f32_e32 v139, v100, v100
	v_fmac_f32_e32 v140, v102, v102
	v_add_f32_e32 v104, v104, v105
	v_add_f32_e32 v105, v131, v138
	v_fmac_f32_e32 v141, v96, v96
	v_fmac_f32_e32 v142, v98, v98
	v_add_f32_e32 v131, v139, v140
	v_add_f32_e32 v104, v104, v105
	v_add_f32_e32 v104, v104, v131
	v_add_f32_e32 v105, v141, v142
	v_add_f32_e32 v104, v104, v105
	ds_bpermute_b32 v105, v176, v104
	v_lshl_add_u64 v[138:139], v[120:121], 2, s[0:1]
	s_waitcnt lgkmcnt(0)
	v_add_f32_e32 v104, v104, v105
	ds_bpermute_b32 v105, v177, v104
	s_mov_b64 s[98:99], vcc
	s_and_saveexec_b64 s[2:3], vcc
	s_cbranch_execz .LBB0_1036
	s_waitcnt lgkmcnt(0)
	v_add_f32_e32 v104, v104, v105
	v_mov_b32_e32 v218, v104
	v_mov_b32_e32 v216, v138
	v_mov_b32_e32 v217, v139
;     __device__ __forceinline__ void fused(f32x4 (&acc)[2][2][4][2], const Unit& u, int wr, int wc, int fr, int fq, PG8_LAS unsigned char* lds, int wid, int lane) const {
;     ...
;             for (int m = 0; m < 4; ++m) { const int row = u.pm * BM + ai * HALF + wr * 64 + m * 16 + fr; const size_t off = (size_t)row * ldc + col0; float ss = 0.f;
; #pragma unroll
;                 for (int bj = 0; bj < 2; ++bj)
; #pragma unroll
;                     for (int n = 0; n < 2; ++n) { const u32x2 w = *(const u32x2*)(xb + off + bj * HALF + n * 16);
;                         const f32x4 bs = (f32x4){__uint_as_float(w.x << 16), __uint_as_float(w.x & 0xffff0000u), __uint_as_float(w.y << 16), __uint_as_float(w.y & 0xffff0000u)};
;                         const f32x4 v = bs + acc[ai][bj][m][n]; acc[ai][bj][m][n] = v; ss += (v[0] * v[0] + v[1] * v[1]) + (v[2] * v[2] + v[3] * v[3]); }
;                 ss += __shfl_xor(ss, 16); ss += __shfl_xor(ss, 32); if (fq == 0) atomicAdd(rowsq + row, ss); }
.LBB0_1036:
	s_or_b64 exec, exec, s[2:3]
	v_or_b32_e32 v104, 32, v130
	s_waitcnt lgkmcnt(0)
	v_ashrrev_i32_e32 v105, 31, v104
	v_lshlrev_b64 v[140:141], 11, v[104:105]
	v_lshl_add_u64 v[140:141], s[96:97], 0, v[140:141]
	v_lshl_add_u64 v[140:141], v[128:129], 1, v[140:141]
	global_load_dwordx2 v[142:143], v[140:141], off
	global_load_dwordx2 v[144:145], v[140:141], off offset:32
	global_load_dwordx2 v[146:147], v[140:141], off offset:256
	s_nop 0
	global_load_dwordx2 v[140:141], v[140:141], off offset:288
	s_and_saveexec_b64 s[2:3], s[98:99]
	global_atomic_add_f32 v[216:217], v218, off
	s_or_b64 exec, exec, s[2:3]
	s_waitcnt vmcnt(4)
	v_lshlrev_b32_e32 v148, 16, v142
	v_and_b32_e32 v149, 0xffff0000, v142
	v_lshlrev_b32_e32 v142, 16, v143
	v_and_b32_e32 v143, 0xffff0000, v143
	s_waitcnt vmcnt(3)
	v_lshlrev_b32_e32 v150, 16, v144
	v_and_b32_e32 v151, 0xffff0000, v144
	v_lshlrev_b32_e32 v144, 16, v145
	v_and_b32_e32 v145, 0xffff0000, v145
	s_waitcnt vmcnt(2)
	v_lshlrev_b32_e32 v152, 16, v146
	v_and_b32_e32 v153, 0xffff0000, v146
	v_lshlrev_b32_e32 v146, 16, v147
	v_and_b32_e32 v147, 0xffff0000, v147
	s_waitcnt vmcnt(1)
	v_lshlrev_b32_e32 v154, 16, v140
	v_and_b32_e32 v155, 0xffff0000, v140
	v_lshlrev_b32_e32 v156, 16, v141
	v_and_b32_e32 v157, 0xffff0000, v141
	v_pk_add_f32 v[94:95], v[94:95], v[142:143]
	v_pk_add_f32 v[140:141], v[92:93], v[148:149]
	v_pk_add_f32 v[90:91], v[90:91], v[144:145]
	v_pk_add_f32 v[92:93], v[88:89], v[150:151]
	v_pk_add_f32 v[86:87], v[86:87], v[146:147]
	v_pk_add_f32 v[84:85], v[84:85], v[152:153]
	v_mul_f32_e32 v88, v141, v141
	v_mul_f32_e32 v89, v95, v95
	v_mul_f32_e32 v121, v93, v93
	v_mul_f32_e32 v131, v91, v91
	v_pk_add_f32 v[82:83], v[82:83], v[156:157]
	v_pk_add_f32 v[80:81], v[80:81], v[154:155]
	v_mul_f32_e32 v142, v85, v85
	v_mul_f32_e32 v143, v87, v87
	v_fmac_f32_e32 v88, v140, v140
	v_fmac_f32_e32 v89, v94, v94
	v_fmac_f32_e32 v121, v92, v92
	v_fmac_f32_e32 v131, v90, v90
	v_mul_f32_e32 v144, v81, v81
	v_mul_f32_e32 v145, v83, v83
	v_fmac_f32_e32 v142, v84, v84
	v_fmac_f32_e32 v143, v86, v86
	v_add_f32_e32 v88, v88, v89
	v_add_f32_e32 v89, v121, v131
	v_fmac_f32_e32 v144, v80, v80
	v_fmac_f32_e32 v145, v82, v82
	v_add_f32_e32 v121, v142, v143
	v_add_f32_e32 v88, v88, v89
	v_add_f32_e32 v88, v88, v121
	v_add_f32_e32 v89, v144, v145
	v_add_f32_e32 v88, v88, v89
	ds_bpermute_b32 v89, v176, v88
	v_lshl_add_u64 v[142:143], v[104:105], 2, s[0:1]
	s_waitcnt lgkmcnt(0)
	v_add_f32_e32 v88, v88, v89
	ds_bpermute_b32 v89, v177, v88
	s_mov_b64 s[98:99], vcc
	s_and_saveexec_b64 s[2:3], vcc
	s_cbranch_execz .LBB0_1038
	s_waitcnt lgkmcnt(0)
	v_add_f32_e32 v88, v88, v89
	v_mov_b32_e32 v218, v88
	v_mov_b32_e32 v216, v142
	v_mov_b32_e32 v217, v143
.LBB0_1038:
	s_or_b64 exec, exec, s[2:3]
	v_or_b32_e32 v88, 48, v130
	s_waitcnt lgkmcnt(0)
	v_ashrrev_i32_e32 v89, 31, v88
	v_lshlrev_b64 v[144:145], 11, v[88:89]
	v_lshl_add_u64 v[144:145], s[96:97], 0, v[144:145]
	v_lshl_add_u64 v[144:145], v[128:129], 1, v[144:145]
	global_load_dwordx2 v[146:147], v[144:145], off
	global_load_dwordx2 v[148:149], v[144:145], off offset:32
	global_load_dwordx2 v[150:151], v[144:145], off offset:256
	s_nop 0
	global_load_dwordx2 v[144:145], v[144:145], off offset:288
	s_and_saveexec_b64 s[2:3], s[98:99]
	global_atomic_add_f32 v[216:217], v218, off
	s_or_b64 exec, exec, s[2:3]
	s_waitcnt vmcnt(4)
	v_lshlrev_b32_e32 v152, 16, v146
	v_and_b32_e32 v153, 0xffff0000, v146
	v_lshlrev_b32_e32 v146, 16, v147
	v_and_b32_e32 v147, 0xffff0000, v147
	s_waitcnt vmcnt(3)
	v_lshlrev_b32_e32 v154, 16, v148
	v_and_b32_e32 v155, 0xffff0000, v148
	v_lshlrev_b32_e32 v148, 16, v149
	v_and_b32_e32 v149, 0xffff0000, v149
	s_waitcnt vmcnt(2)
	v_lshlrev_b32_e32 v156, 16, v150
	v_and_b32_e32 v157, 0xffff0000, v150
	v_lshlrev_b32_e32 v150, 16, v151
	v_and_b32_e32 v151, 0xffff0000, v151
	s_waitcnt vmcnt(1)
	v_lshlrev_b32_e32 v158, 16, v144
	v_and_b32_e32 v159, 0xffff0000, v144
	v_lshlrev_b32_e32 v160, 16, v145
	v_and_b32_e32 v161, 0xffff0000, v145
	v_pk_add_f32 v[78:79], v[78:79], v[146:147]
	v_pk_add_f32 v[144:145], v[76:77], v[152:153]
	v_pk_add_f32 v[74:75], v[74:75], v[148:149]
	v_pk_add_f32 v[76:77], v[72:73], v[154:155]
	v_pk_add_f32 v[70:71], v[70:71], v[150:151]
	v_pk_add_f32 v[68:69], v[68:69], v[156:157]
	v_mul_f32_e32 v72, v145, v145
	v_mul_f32_e32 v73, v79, v79
	v_mul_f32_e32 v105, v77, v77
	v_mul_f32_e32 v121, v75, v75
	v_pk_add_f32 v[66:67], v[66:67], v[160:161]
	v_pk_add_f32 v[64:65], v[64:65], v[158:159]
	v_mul_f32_e32 v131, v69, v69
	v_mul_f32_e32 v146, v71, v71
	v_fmac_f32_e32 v72, v144, v144
	v_fmac_f32_e32 v73, v78, v78
	v_fmac_f32_e32 v105, v76, v76
	v_fmac_f32_e32 v121, v74, v74
	v_mul_f32_e32 v147, v65, v65
	v_mul_f32_e32 v148, v67, v67
	v_fmac_f32_e32 v131, v68, v68
	v_fmac_f32_e32 v146, v70, v70
	v_add_f32_e32 v72, v72, v73
	v_add_f32_e32 v73, v105, v121
	v_fmac_f32_e32 v147, v64, v64
	v_fmac_f32_e32 v148, v66, v66
	v_add_f32_e32 v105, v131, v146
	v_add_f32_e32 v72, v72, v73
	v_add_f32_e32 v72, v72, v105
	v_add_f32_e32 v73, v147, v148
	v_add_f32_e32 v72, v72, v73
	ds_bpermute_b32 v73, v176, v72
	v_lshl_add_u64 v[146:147], v[88:89], 2, s[0:1]
	s_waitcnt lgkmcnt(0)
	v_add_f32_e32 v72, v72, v73
	ds_bpermute_b32 v73, v177, v72
	s_mov_b64 s[98:99], vcc
	s_and_saveexec_b64 s[2:3], vcc
	s_cbranch_execz .LBB0_1040
	s_waitcnt lgkmcnt(0)
	v_add_f32_e32 v72, v72, v73
	v_mov_b32_e32 v218, v72
	v_mov_b32_e32 v216, v146
	v_mov_b32_e32 v217, v147
;     __device__ __forceinline__ void fused(f32x4 (&acc)[2][2][4][2], const Unit& u, int wr, int wc, int fr, int fq, PG8_LAS unsigned char* lds, int wid, int lane) const {
;     ...
;             for (int m = 0; m < 4; ++m) { const int row = u.pm * BM + ai * HALF + wr * 64 + m * 16 + fr; const size_t off = (size_t)row * ldc + col0; float ss = 0.f;
; #pragma unroll
;                 for (int bj = 0; bj < 2; ++bj)
; #pragma unroll
;                     for (int n = 0; n < 2; ++n) { const u32x2 w = *(const u32x2*)(xb + off + bj * HALF + n * 16);
;                         const f32x4 bs = (f32x4){__uint_as_float(w.x << 16), __uint_as_float(w.x & 0xffff0000u), __uint_as_float(w.y << 16), __uint_as_float(w.y & 0xffff0000u)};
;                         const f32x4 v = bs + acc[ai][bj][m][n]; acc[ai][bj][m][n] = v; ss += (v[0] * v[0] + v[1] * v[1]) + (v[2] * v[2] + v[3] * v[3]); }
;                 ss += __shfl_xor(ss, 16); ss += __shfl_xor(ss, 32); if (fq == 0) atomicAdd(rowsq + row, ss); }
.LBB0_1040:
	s_or_b64 exec, exec, s[2:3]
	v_add_u32_e32 v72, 0x80, v130
	s_waitcnt lgkmcnt(0)
	v_ashrrev_i32_e32 v73, 31, v72
	v_lshlrev_b64 v[148:149], 11, v[72:73]
	v_lshl_add_u64 v[148:149], s[96:97], 0, v[148:149]
	v_lshl_add_u64 v[148:149], v[128:129], 1, v[148:149]
	global_load_dwordx2 v[150:151], v[148:149], off
	global_load_dwordx2 v[152:153], v[148:149], off offset:32
	global_load_dwordx2 v[154:155], v[148:149], off offset:256
	s_nop 0
	global_load_dwordx2 v[148:149], v[148:149], off offset:288
	s_and_saveexec_b64 s[2:3], s[98:99]
	global_atomic_add_f32 v[216:217], v218, off
	s_or_b64 exec, exec, s[2:3]
	s_waitcnt vmcnt(4)
	v_lshlrev_b32_e32 v156, 16, v150
	v_and_b32_e32 v157, 0xffff0000, v150
	v_lshlrev_b32_e32 v150, 16, v151
	v_and_b32_e32 v151, 0xffff0000, v151
	s_waitcnt vmcnt(3)
	v_lshlrev_b32_e32 v158, 16, v152
	v_and_b32_e32 v159, 0xffff0000, v152
	v_lshlrev_b32_e32 v152, 16, v153
	v_and_b32_e32 v153, 0xffff0000, v153
	s_waitcnt vmcnt(2)
	v_lshlrev_b32_e32 v160, 16, v154
	v_and_b32_e32 v161, 0xffff0000, v154
	v_lshlrev_b32_e32 v154, 16, v155
	v_and_b32_e32 v155, 0xffff0000, v155
	s_waitcnt vmcnt(1)
	v_lshlrev_b32_e32 v162, 16, v148
	v_and_b32_e32 v163, 0xffff0000, v148
	v_lshlrev_b32_e32 v164, 16, v149
	v_and_b32_e32 v165, 0xffff0000, v149
	v_pk_add_f32 v[62:63], v[62:63], v[150:151]
	v_pk_add_f32 v[148:149], v[60:61], v[156:157]
	v_pk_add_f32 v[58:59], v[58:59], v[152:153]
	v_pk_add_f32 v[60:61], v[56:57], v[158:159]
	v_pk_add_f32 v[54:55], v[54:55], v[154:155]
	v_pk_add_f32 v[52:53], v[52:53], v[160:161]
	v_mul_f32_e32 v56, v149, v149
	v_mul_f32_e32 v57, v63, v63
	v_mul_f32_e32 v89, v61, v61
	v_mul_f32_e32 v105, v59, v59
	v_pk_add_f32 v[50:51], v[50:51], v[164:165]
	v_pk_add_f32 v[48:49], v[48:49], v[162:163]
	v_mul_f32_e32 v121, v53, v53
	v_mul_f32_e32 v131, v55, v55
	v_fmac_f32_e32 v56, v148, v148
	v_fmac_f32_e32 v57, v62, v62
	v_fmac_f32_e32 v89, v60, v60
	v_fmac_f32_e32 v105, v58, v58
	v_mul_f32_e32 v150, v49, v49
	v_mul_f32_e32 v151, v51, v51
	v_fmac_f32_e32 v121, v52, v52
	v_fmac_f32_e32 v131, v54, v54
	v_add_f32_e32 v56, v56, v57
	v_add_f32_e32 v57, v89, v105
	v_fmac_f32_e32 v150, v48, v48
	v_fmac_f32_e32 v151, v50, v50
	v_add_f32_e32 v89, v121, v131
	v_add_f32_e32 v56, v56, v57
	v_add_f32_e32 v56, v56, v89
	v_add_f32_e32 v57, v150, v151
	v_add_f32_e32 v56, v56, v57
	ds_bpermute_b32 v57, v176, v56
	v_lshl_add_u64 v[150:151], v[72:73], 2, s[0:1]
	s_waitcnt lgkmcnt(0)
	v_add_f32_e32 v56, v56, v57
	ds_bpermute_b32 v57, v177, v56
	s_mov_b64 s[98:99], vcc
	s_and_saveexec_b64 s[2:3], vcc
	s_cbranch_execz .LBB0_1042
	s_waitcnt lgkmcnt(0)
	v_add_f32_e32 v56, v56, v57
	v_mov_b32_e32 v218, v56
	v_mov_b32_e32 v216, v150
	v_mov_b32_e32 v217, v151
.LBB0_1042:
	s_or_b64 exec, exec, s[2:3]
	v_add_u32_e32 v56, 0x90, v130
	s_waitcnt lgkmcnt(0)
	v_ashrrev_i32_e32 v57, 31, v56
	v_lshlrev_b64 v[152:153], 11, v[56:57]
	v_lshl_add_u64 v[152:153], s[96:97], 0, v[152:153]
	v_lshl_add_u64 v[152:153], v[128:129], 1, v[152:153]
	global_load_dwordx2 v[154:155], v[152:153], off
	global_load_dwordx2 v[156:157], v[152:153], off offset:32
	global_load_dwordx2 v[158:159], v[152:153], off offset:256
	s_nop 0
	global_load_dwordx2 v[152:153], v[152:153], off offset:288
	s_and_saveexec_b64 s[2:3], s[98:99]
	global_atomic_add_f32 v[216:217], v218, off
	s_or_b64 exec, exec, s[2:3]
	s_waitcnt vmcnt(4)
	v_lshlrev_b32_e32 v160, 16, v154
	v_and_b32_e32 v161, 0xffff0000, v154
	v_lshlrev_b32_e32 v154, 16, v155
	v_and_b32_e32 v155, 0xffff0000, v155
	s_waitcnt vmcnt(3)
	v_lshlrev_b32_e32 v162, 16, v156
	v_and_b32_e32 v163, 0xffff0000, v156
	v_lshlrev_b32_e32 v156, 16, v157
	v_and_b32_e32 v157, 0xffff0000, v157
	s_waitcnt vmcnt(2)
	v_lshlrev_b32_e32 v164, 16, v158
	v_and_b32_e32 v165, 0xffff0000, v158
	v_lshlrev_b32_e32 v158, 16, v159
	v_and_b32_e32 v159, 0xffff0000, v159
	s_waitcnt vmcnt(1)
	v_lshlrev_b32_e32 v166, 16, v152
	v_and_b32_e32 v167, 0xffff0000, v152
	v_lshlrev_b32_e32 v168, 16, v153
	v_and_b32_e32 v169, 0xffff0000, v153
	v_pk_add_f32 v[46:47], v[46:47], v[154:155]
	v_pk_add_f32 v[152:153], v[44:45], v[160:161]
	v_pk_add_f32 v[42:43], v[42:43], v[156:157]
	v_pk_add_f32 v[44:45], v[40:41], v[162:163]
	v_pk_add_f32 v[38:39], v[38:39], v[158:159]
	v_pk_add_f32 v[36:37], v[36:37], v[164:165]
	v_mul_f32_e32 v40, v153, v153
	v_mul_f32_e32 v41, v47, v47
	v_mul_f32_e32 v73, v45, v45
	v_mul_f32_e32 v89, v43, v43
	v_pk_add_f32 v[34:35], v[34:35], v[168:169]
	v_pk_add_f32 v[32:33], v[32:33], v[166:167]
	v_mul_f32_e32 v105, v37, v37
	v_mul_f32_e32 v121, v39, v39
	v_fmac_f32_e32 v40, v152, v152
	v_fmac_f32_e32 v41, v46, v46
	v_fmac_f32_e32 v73, v44, v44
	v_fmac_f32_e32 v89, v42, v42
	v_mul_f32_e32 v131, v33, v33
	v_mul_f32_e32 v154, v35, v35
	v_fmac_f32_e32 v105, v36, v36
	v_fmac_f32_e32 v121, v38, v38
	v_add_f32_e32 v40, v40, v41
	v_add_f32_e32 v41, v73, v89
	v_fmac_f32_e32 v131, v32, v32
	v_fmac_f32_e32 v154, v34, v34
	v_add_f32_e32 v73, v105, v121
	v_add_f32_e32 v40, v40, v41
	v_add_f32_e32 v40, v40, v73
	v_add_f32_e32 v41, v131, v154
	v_add_f32_e32 v40, v40, v41
	ds_bpermute_b32 v41, v176, v40
	v_lshl_add_u64 v[154:155], v[56:57], 2, s[0:1]
	s_waitcnt lgkmcnt(0)
	v_add_f32_e32 v40, v40, v41
	ds_bpermute_b32 v41, v177, v40
	s_mov_b64 s[98:99], vcc
	s_and_saveexec_b64 s[2:3], vcc
	s_cbranch_execz .LBB0_1044
	s_waitcnt lgkmcnt(0)
	v_add_f32_e32 v40, v40, v41
	v_mov_b32_e32 v218, v40
	v_mov_b32_e32 v216, v154
	v_mov_b32_e32 v217, v155
;     __device__ __forceinline__ void fused(f32x4 (&acc)[2][2][4][2], const Unit& u, int wr, int wc, int fr, int fq, PG8_LAS unsigned char* lds, int wid, int lane) const {
;     ...
;             for (int m = 0; m < 4; ++m) { const int row = u.pm * BM + ai * HALF + wr * 64 + m * 16 + fr; const size_t off = (size_t)row * ldc + col0; float ss = 0.f;
; #pragma unroll
;                 for (int bj = 0; bj < 2; ++bj)
; #pragma unroll
;                     for (int n = 0; n < 2; ++n) { const u32x2 w = *(const u32x2*)(xb + off + bj * HALF + n * 16);
;                         const f32x4 bs = (f32x4){__uint_as_float(w.x << 16), __uint_as_float(w.x & 0xffff0000u), __uint_as_float(w.y << 16), __uint_as_float(w.y & 0xffff0000u)};
;                         const f32x4 v = bs + acc[ai][bj][m][n]; acc[ai][bj][m][n] = v; ss += (v[0] * v[0] + v[1] * v[1]) + (v[2] * v[2] + v[3] * v[3]); }
;                 ss += __shfl_xor(ss, 16); ss += __shfl_xor(ss, 32); if (fq == 0) atomicAdd(rowsq + row, ss); }
.LBB0_1044:
	s_or_b64 exec, exec, s[2:3]
	v_add_u32_e32 v40, 0xa0, v130
	s_waitcnt lgkmcnt(0)
	v_ashrrev_i32_e32 v41, 31, v40
	v_lshlrev_b64 v[156:157], 11, v[40:41]
	v_lshl_add_u64 v[156:157], s[96:97], 0, v[156:157]
	v_lshl_add_u64 v[156:157], v[128:129], 1, v[156:157]
	global_load_dwordx2 v[158:159], v[156:157], off
	global_load_dwordx2 v[160:161], v[156:157], off offset:32
	global_load_dwordx2 v[162:163], v[156:157], off offset:256
	s_nop 0
	global_load_dwordx2 v[156:157], v[156:157], off offset:288
	s_and_saveexec_b64 s[2:3], s[98:99]
	global_atomic_add_f32 v[216:217], v218, off
	s_or_b64 exec, exec, s[2:3]
	s_waitcnt vmcnt(4)
	v_lshlrev_b32_e32 v164, 16, v158
	v_and_b32_e32 v165, 0xffff0000, v158
	v_lshlrev_b32_e32 v158, 16, v159
	v_and_b32_e32 v159, 0xffff0000, v159
	s_waitcnt vmcnt(3)
	v_lshlrev_b32_e32 v166, 16, v160
	v_and_b32_e32 v167, 0xffff0000, v160
	v_lshlrev_b32_e32 v160, 16, v161
	v_and_b32_e32 v161, 0xffff0000, v161
	s_waitcnt vmcnt(2)
	v_lshlrev_b32_e32 v168, 16, v162
	v_and_b32_e32 v169, 0xffff0000, v162
	v_lshlrev_b32_e32 v162, 16, v163
	v_and_b32_e32 v163, 0xffff0000, v163
	s_waitcnt vmcnt(1)
	v_lshlrev_b32_e32 v170, 16, v156
	v_and_b32_e32 v171, 0xffff0000, v156
	v_lshlrev_b32_e32 v172, 16, v157
	v_and_b32_e32 v173, 0xffff0000, v157
	v_pk_add_f32 v[30:31], v[30:31], v[158:159]
	v_pk_add_f32 v[156:157], v[28:29], v[164:165]
	v_pk_add_f32 v[26:27], v[26:27], v[160:161]
	v_pk_add_f32 v[28:29], v[24:25], v[166:167]
	v_pk_add_f32 v[22:23], v[22:23], v[162:163]
	v_pk_add_f32 v[20:21], v[20:21], v[168:169]
	v_mul_f32_e32 v24, v157, v157
	v_mul_f32_e32 v25, v31, v31
	v_mul_f32_e32 v57, v29, v29
	v_mul_f32_e32 v73, v27, v27
	v_pk_add_f32 v[18:19], v[18:19], v[172:173]
	v_pk_add_f32 v[16:17], v[16:17], v[170:171]
	v_mul_f32_e32 v89, v21, v21
	v_mul_f32_e32 v105, v23, v23
	v_fmac_f32_e32 v24, v156, v156
	v_fmac_f32_e32 v25, v30, v30
	v_fmac_f32_e32 v57, v28, v28
	v_fmac_f32_e32 v73, v26, v26
	v_mul_f32_e32 v121, v17, v17
	v_mul_f32_e32 v131, v19, v19
	v_fmac_f32_e32 v89, v20, v20
	v_fmac_f32_e32 v105, v22, v22
	v_add_f32_e32 v24, v24, v25
	v_add_f32_e32 v25, v57, v73
	v_fmac_f32_e32 v121, v16, v16
	v_fmac_f32_e32 v131, v18, v18
	v_add_f32_e32 v57, v89, v105
	v_add_f32_e32 v24, v24, v25
	v_add_f32_e32 v24, v24, v57
	v_add_f32_e32 v25, v121, v131
	v_add_f32_e32 v24, v24, v25
	ds_bpermute_b32 v25, v176, v24
	v_lshl_add_u64 v[164:165], v[40:41], 2, s[0:1]
	s_waitcnt lgkmcnt(0)
	v_add_f32_e32 v24, v24, v25
	ds_bpermute_b32 v25, v177, v24
	s_mov_b64 s[98:99], vcc
	s_and_saveexec_b64 s[2:3], vcc
	s_cbranch_execz .LBB0_1046
	s_waitcnt lgkmcnt(0)
	v_add_f32_e32 v24, v24, v25
	v_mov_b32_e32 v218, v24
	v_mov_b32_e32 v216, v164
	v_mov_b32_e32 v217, v165
.LBB0_1046:
	s_or_b64 exec, exec, s[2:3]
	v_add_u32_e32 v24, 0xb0, v130
	s_waitcnt lgkmcnt(0)
	v_ashrrev_i32_e32 v25, 31, v24
	v_lshlrev_b64 v[158:159], 11, v[24:25]
	v_lshl_add_u64 v[158:159], s[96:97], 0, v[158:159]
	v_lshl_add_u64 v[158:159], v[128:129], 1, v[158:159]
	global_load_dwordx2 v[160:161], v[158:159], off
	global_load_dwordx2 v[162:163], v[158:159], off offset:32
	global_load_dwordx2 v[166:167], v[158:159], off offset:256
	s_nop 0
	global_load_dwordx2 v[158:159], v[158:159], off offset:288
	s_and_saveexec_b64 s[2:3], s[98:99]
	global_atomic_add_f32 v[216:217], v218, off
	s_or_b64 exec, exec, s[2:3]
	s_waitcnt vmcnt(4)
	v_lshlrev_b32_e32 v168, 16, v160
	v_and_b32_e32 v169, 0xffff0000, v160
	v_lshlrev_b32_e32 v160, 16, v161
	v_and_b32_e32 v161, 0xffff0000, v161
	s_waitcnt vmcnt(3)
	v_lshlrev_b32_e32 v170, 16, v162
	v_and_b32_e32 v171, 0xffff0000, v162
	v_lshlrev_b32_e32 v162, 16, v163
	v_and_b32_e32 v163, 0xffff0000, v163
	s_waitcnt vmcnt(2)
	v_lshlrev_b32_e32 v178, 16, v166
	v_and_b32_e32 v179, 0xffff0000, v166
	v_lshlrev_b32_e32 v166, 16, v167
	v_and_b32_e32 v167, 0xffff0000, v167
	s_waitcnt vmcnt(1)
	v_lshlrev_b32_e32 v180, 16, v158
	v_and_b32_e32 v181, 0xffff0000, v158
	v_lshlrev_b32_e32 v158, 16, v159
	v_and_b32_e32 v159, 0xffff0000, v159
	v_pk_add_f32 v[172:173], v[14:15], v[160:161]
	v_pk_add_f32 v[174:175], v[12:13], v[168:169]
	v_pk_add_f32 v[168:169], v[10:11], v[162:163]
	v_pk_add_f32 v[170:171], v[8:9], v[170:171]
	v_pk_add_f32 v[160:161], v[6:7], v[166:167]
	v_pk_add_f32 v[166:167], v[4:5], v[178:179]
	v_pk_add_f32 v[158:159], v[2:3], v[158:159]
	v_pk_add_f32 v[162:163], v[0:1], v[180:181]
	v_mul_f32_e32 v0, v175, v175
	v_mul_f32_e32 v1, v173, v173
	v_mul_f32_e32 v2, v171, v171
	v_mul_f32_e32 v3, v169, v169
	v_mul_f32_e32 v4, v167, v167
	v_mul_f32_e32 v5, v161, v161
	v_fmac_f32_e32 v0, v174, v174
	v_fmac_f32_e32 v1, v172, v172
	v_fmac_f32_e32 v2, v170, v170
	v_fmac_f32_e32 v3, v168, v168
	v_mul_f32_e32 v6, v163, v163
	v_mul_f32_e32 v7, v159, v159
	v_fmac_f32_e32 v4, v166, v166
	v_fmac_f32_e32 v5, v160, v160
	v_add_f32_e32 v0, v0, v1
	v_add_f32_e32 v1, v2, v3
	v_fmac_f32_e32 v6, v162, v162
	v_fmac_f32_e32 v7, v158, v158
	v_add_f32_e32 v2, v4, v5
	v_add_f32_e32 v0, v0, v1
	v_add_f32_e32 v0, v0, v2
	v_add_f32_e32 v1, v6, v7
	v_add_f32_e32 v0, v0, v1
	ds_bpermute_b32 v1, v176, v0
	s_waitcnt lgkmcnt(0)
	v_add_f32_e32 v0, v0, v1
	ds_bpermute_b32 v1, v177, v0
	v_lshl_add_u64 v[176:177], v[24:25], 2, s[0:1]
	s_and_saveexec_b64 s[0:1], vcc
	s_cbranch_execz .LBB0_1048
	s_waitcnt lgkmcnt(0)
	v_add_f32_e32 v0, v0, v1
	global_atomic_add_f32 v[176:177], v0, off
